# dense attention ping-pong with ONE barrier per tile (group A after VALU seg, group B after MFMA seg), segments free-running
# speedup vs baseline: 1.0093x; 1.0093x over previous
.LBB0_1013:
	s_waitcnt lgkmcnt(1)
	v_mfma_f32_32x32x16_bf16 v[50:65], v[226:229], v[170:173], v[50:65]
	ds_read_b128 v[246:249], v235 offset:32
	v_mfma_f32_32x32x16_bf16 v[16:31], v[226:229], v[174:177], v[16:31]
	s_add_i32 s44, s4, 1
	s_and_b32 s43, s44, 1
	s_mul_i32 s43, s43, 0x2400
	s_waitcnt lgkmcnt(1)
	v_mfma_f32_32x32x16_bf16 v[34:49], v[230:233], v[170:173], v[34:49]
	ds_read_b128 v[226:229], v235 offset:4640
	v_add_u32_e32 v198, s43, v203
	v_add_u32_e32 v199, s42, v203
	v_mfma_f32_32x32x16_bf16 v[0:15], v[230:233], v[174:177], v[0:15]
	s_add_i32 s16, s4, 2
	s_min_u32 s16, s16, 63
	s_waitcnt lgkmcnt(1)
	v_mfma_f32_32x32x16_bf16 v[50:65], v[246:249], v[166:169], v[50:65]
	ds_read_b128 v[230:233], v235 offset:64
	v_mfma_f32_32x32x16_bf16 v[16:31], v[246:249], v[162:165], v[16:31]
	s_waitcnt lgkmcnt(1)
	v_mfma_f32_32x32x16_bf16 v[34:49], v[226:229], v[166:169], v[34:49]
	ds_read_b128 v[246:249], v235 offset:4672
	v_mfma_f32_32x32x16_bf16 v[0:15], v[226:229], v[162:165], v[0:15]
	s_waitcnt lgkmcnt(1)
	v_mfma_f32_32x32x16_bf16 v[50:65], v[230:233], v[186:189], v[50:65]
	ds_read_b128 v[226:229], v235 offset:96
	v_mfma_f32_32x32x16_bf16 v[16:31], v[230:233], v[218:221], v[16:31]
	s_waitcnt lgkmcnt(1)
	v_mfma_f32_32x32x16_bf16 v[34:49], v[246:249], v[186:189], v[34:49]
	ds_read_b128 v[230:233], v235 offset:4704
	v_mfma_f32_32x32x16_bf16 v[0:15], v[246:249], v[218:221], v[0:15]
	s_waitcnt lgkmcnt(1)
	v_mfma_f32_32x32x16_bf16 v[50:65], v[226:229], v[190:193], v[50:65]
	ds_read_b128 v[246:249], v234
	v_mfma_f32_32x32x16_bf16 v[16:31], v[226:229], v[222:225], v[16:31]
	s_waitcnt lgkmcnt(1)
	v_mfma_f32_32x32x16_bf16 v[34:49], v[230:233], v[190:193], v[34:49]
	ds_read_b128 v[226:229], v234 offset:32
	v_mfma_f32_32x32x16_bf16 v[0:15], v[230:233], v[222:225], v[0:15]
	s_waitcnt lgkmcnt(1)
	v_mfma_f32_32x32x16_bf16 v[114:129], v[246:249], v[130:133], 0
	ds_read_b128 v[230:233], v234 offset:64
	v_mfma_f32_32x32x16_bf16 v[98:113], v[246:249], v[146:149], 0
	s_waitcnt lgkmcnt(1)
	v_mfma_f32_32x32x16_bf16 v[114:129], v[226:229], v[134:137], v[114:129]
	ds_read_b128 v[246:249], v234 offset:96
	s_waitcnt vmcnt(0)
	ds_write_b128 v199, v[178:181]
	v_mfma_f32_32x32x16_bf16 v[98:113], v[226:229], v[150:153], v[98:113]
	s_waitcnt lgkmcnt(2)
	v_mfma_f32_32x32x16_bf16 v[114:129], v[230:233], v[138:141], v[114:129]
	ds_read_b128 v[226:229], v234 offset:4608
	ds_write_b128 v198, v[182:185]
	v_mfma_f32_32x32x16_bf16 v[98:113], v[230:233], v[154:157], v[98:113]
	s_waitcnt lgkmcnt(3)
	v_mfma_f32_32x32x16_bf16 v[114:129], v[246:249], v[142:145], v[114:129]
	ds_read_b128 v[230:233], v234 offset:4640
	s_lshl_b64 s[6:7], s[16:17], 13
	v_lshl_add_u64 v[182:183], v[212:213], 0, s[6:7]
	v_mfma_f32_32x32x16_bf16 v[98:113], v[246:249], v[158:161], v[98:113]
	global_load_dwordx4 v[182:185], v[182:183], off
	s_lshl_b64 s[6:7], s[16:17], 7
	s_waitcnt lgkmcnt(2)
	v_mfma_f32_32x32x16_bf16 v[82:97], v[226:229], v[130:133], 0
	ds_read_b128 v[246:249], v234 offset:4672
	v_lshl_add_u64 v[178:179], v[214:215], 0, s[6:7]
	v_mfma_f32_32x32x16_bf16 v[66:81], v[226:229], v[146:149], 0
	global_load_dwordx4 v[178:181], v[178:179], off
	s_waitcnt lgkmcnt(1)
	v_mfma_f32_32x32x16_bf16 v[82:97], v[230:233], v[134:137], v[82:97]
	ds_read_b128 v[226:229], v234 offset:4704
	v_mfma_f32_32x32x16_bf16 v[66:81], v[230:233], v[150:153], v[66:81]
	s_waitcnt lgkmcnt(1)
	v_mfma_f32_32x32x16_bf16 v[82:97], v[246:249], v[138:141], v[82:97]
	v_mfma_f32_32x32x16_bf16 v[66:81], v[246:249], v[154:157], v[66:81]
	s_waitcnt lgkmcnt(0)
	v_mfma_f32_32x32x16_bf16 v[82:97], v[226:229], v[142:145], v[82:97]
	v_mfma_f32_32x32x16_bf16 v[66:81], v[226:229], v[158:161], v[66:81]
	s_cmp_eq_u32 s101, 1
	s_cbranch_scc0 .Lpp_nb_l1
	s_barrier
.Lpp_nb_l1:
	v_exp_f32_e32 v114, v114
	v_exp_f32_e32 v115, v115
	v_exp_f32_e32 v116, v116
	v_exp_f32_e32 v117, v117
	v_exp_f32_e32 v118, v118
	v_exp_f32_e32 v119, v119
	v_exp_f32_e32 v120, v120
	v_exp_f32_e32 v121, v121
	v_cvt_pk_bf16_f32 v170, v114, v115
	v_add_f32_e32 v114, v114, v115
	v_exp_f32_e32 v122, v122
	v_exp_f32_e32 v123, v123
	v_cvt_pk_bf16_f32 v171, v116, v117
	v_add_f32_e32 v116, v116, v117
	v_add_f32_e32 v217, v217, v114
	v_exp_f32_e32 v124, v124
	v_exp_f32_e32 v125, v125
	v_cvt_pk_bf16_f32 v172, v118, v119
	v_add_f32_e32 v118, v118, v119
	v_add_f32_e32 v217, v217, v116
	v_exp_f32_e32 v126, v126
	v_exp_f32_e32 v127, v127
	v_cvt_pk_bf16_f32 v173, v120, v121
	v_add_f32_e32 v120, v120, v121
	v_add_f32_e32 v217, v217, v118
	v_exp_f32_e32 v128, v128
	v_exp_f32_e32 v129, v129
	v_cvt_pk_bf16_f32 v166, v122, v123
	v_add_f32_e32 v122, v122, v123
	v_add_f32_e32 v217, v217, v120
	v_exp_f32_e32 v98, v98
	v_exp_f32_e32 v99, v99
	v_cvt_pk_bf16_f32 v167, v124, v125
	v_add_f32_e32 v124, v124, v125
	v_add_f32_e32 v217, v217, v122
	v_exp_f32_e32 v100, v100
	v_exp_f32_e32 v101, v101
	v_cvt_pk_bf16_f32 v168, v126, v127
	v_add_f32_e32 v126, v126, v127
	v_add_f32_e32 v217, v217, v124
	v_exp_f32_e32 v102, v102
	v_exp_f32_e32 v103, v103
	v_cvt_pk_bf16_f32 v169, v128, v129
	v_add_f32_e32 v128, v128, v129
	v_add_f32_e32 v217, v217, v126
	v_exp_f32_e32 v104, v104
	v_exp_f32_e32 v105, v105
	v_cvt_pk_bf16_f32 v174, v98, v99
	v_add_f32_e32 v98, v98, v99
	v_add_f32_e32 v217, v217, v128
	v_exp_f32_e32 v106, v106
	v_exp_f32_e32 v107, v107
	v_cvt_pk_bf16_f32 v175, v100, v101
	v_add_f32_e32 v100, v100, v101
	v_add_f32_e32 v216, v216, v98
	v_exp_f32_e32 v108, v108
	v_exp_f32_e32 v109, v109
	v_cvt_pk_bf16_f32 v176, v102, v103
	v_add_f32_e32 v102, v102, v103
	v_add_f32_e32 v216, v216, v100
	v_exp_f32_e32 v110, v110
	v_exp_f32_e32 v111, v111
	v_cvt_pk_bf16_f32 v177, v104, v105
	v_add_f32_e32 v104, v104, v105
	v_add_f32_e32 v216, v216, v102
	v_exp_f32_e32 v112, v112
	v_exp_f32_e32 v113, v113
	v_cvt_pk_bf16_f32 v162, v106, v107
	v_add_f32_e32 v106, v106, v107
	v_add_f32_e32 v216, v216, v104
	v_cvt_pk_bf16_f32 v163, v108, v109
	v_add_f32_e32 v108, v108, v109
	v_add_f32_e32 v216, v216, v106
	v_cvt_pk_bf16_f32 v164, v110, v111
	v_add_f32_e32 v110, v110, v111
	v_add_f32_e32 v216, v216, v108
	v_cvt_pk_bf16_f32 v165, v112, v113
	v_add_f32_e32 v112, v112, v113
	v_add_f32_e32 v216, v216, v110
	v_add_f32_e32 v216, v216, v112
	v_exp_f32_e32 v82, v82
	v_exp_f32_e32 v83, v83
	v_exp_f32_e32 v84, v84
	v_exp_f32_e32 v85, v85
	v_exp_f32_e32 v86, v86
	v_exp_f32_e32 v87, v87
	v_exp_f32_e32 v88, v88
	v_exp_f32_e32 v89, v89
	v_cvt_pk_bf16_f32 v186, v82, v83
	v_add_f32_e32 v82, v82, v83
	v_exp_f32_e32 v90, v90
	v_exp_f32_e32 v91, v91
	v_cvt_pk_bf16_f32 v187, v84, v85
	v_add_f32_e32 v84, v84, v85
	v_add_f32_e32 v217, v217, v82
	v_exp_f32_e32 v92, v92
	v_exp_f32_e32 v93, v93
	v_cvt_pk_bf16_f32 v188, v86, v87
	v_add_f32_e32 v86, v86, v87
	v_add_f32_e32 v217, v217, v84
	v_exp_f32_e32 v94, v94
	v_exp_f32_e32 v95, v95
	v_cvt_pk_bf16_f32 v189, v88, v89
	v_add_f32_e32 v88, v88, v89
	v_add_f32_e32 v217, v217, v86
	v_exp_f32_e32 v96, v96
	v_exp_f32_e32 v97, v97
	v_cvt_pk_bf16_f32 v190, v90, v91
	v_add_f32_e32 v90, v90, v91
	v_add_f32_e32 v217, v217, v88
	v_exp_f32_e32 v66, v66
	v_exp_f32_e32 v67, v67
	v_cvt_pk_bf16_f32 v191, v92, v93
	v_add_f32_e32 v92, v92, v93
	v_add_f32_e32 v217, v217, v90
	v_exp_f32_e32 v68, v68
	v_exp_f32_e32 v69, v69
	v_cvt_pk_bf16_f32 v192, v94, v95
	v_add_f32_e32 v94, v94, v95
	v_add_f32_e32 v217, v217, v92
	v_exp_f32_e32 v70, v70
	v_exp_f32_e32 v71, v71
	v_cvt_pk_bf16_f32 v193, v96, v97
	v_add_f32_e32 v96, v96, v97
	v_add_f32_e32 v217, v217, v94
	v_exp_f32_e32 v72, v72
	v_exp_f32_e32 v73, v73
	v_cvt_pk_bf16_f32 v218, v66, v67
	v_add_f32_e32 v66, v66, v67
	v_add_f32_e32 v217, v217, v96
	v_exp_f32_e32 v74, v74
	v_exp_f32_e32 v75, v75
	v_cvt_pk_bf16_f32 v219, v68, v69
	v_add_f32_e32 v68, v68, v69
	v_add_f32_e32 v216, v216, v66
	v_exp_f32_e32 v76, v76
	v_exp_f32_e32 v77, v77
	v_cvt_pk_bf16_f32 v220, v70, v71
	v_add_f32_e32 v70, v70, v71
	v_add_f32_e32 v216, v216, v68
	v_exp_f32_e32 v78, v78
	v_exp_f32_e32 v79, v79
	v_cvt_pk_bf16_f32 v221, v72, v73
	v_add_f32_e32 v72, v72, v73
	v_add_f32_e32 v216, v216, v70
	v_exp_f32_e32 v80, v80
	v_exp_f32_e32 v81, v81
	v_cvt_pk_bf16_f32 v222, v74, v75
	v_add_f32_e32 v74, v74, v75
	v_add_f32_e32 v216, v216, v72
	v_cvt_pk_bf16_f32 v223, v76, v77
	v_add_f32_e32 v76, v76, v77
	v_add_f32_e32 v216, v216, v74
	v_cvt_pk_bf16_f32 v224, v78, v79
	v_add_f32_e32 v78, v78, v79
	v_add_f32_e32 v216, v216, v76
	v_cvt_pk_bf16_f32 v225, v80, v81
	v_add_f32_e32 v80, v80, v81
	v_add_f32_e32 v216, v216, v78
	v_add_f32_e32 v216, v216, v80
	v_add_u32_e32 v235, s41, v32
	v_add_u32_e32 v234, s43, v245
	ds_read_b128 v[226:229], v235
	ds_read_b128 v[230:233], v235 offset:4608
	s_waitcnt lgkmcnt(2)
	s_mov_b32 s6, s5
	s_mov_b32 s5, s41
	s_mov_b32 s41, s42
	s_mov_b32 s42, s6
	s_mov_b32 s4, s44
	s_cmp_eq_u32 s101, 0
	s_cbranch_scc0 .Lpp_nb_l2
	s_barrier
.Lpp_nb_l2:
	s_cmp_eq_u32 s44, 63
	s_cbranch_scc0 .LBB0_1013
	s_waitcnt lgkmcnt(1)
	v_mfma_f32_32x32x16_bf16 v[50:65], v[226:229], v[170:173], v[50:65]
	ds_read_b128 v[246:249], v235 offset:32
	v_mfma_f32_32x32x16_bf16 v[16:31], v[226:229], v[174:177], v[16:31]
	s_waitcnt lgkmcnt(1)
	v_mfma_f32_32x32x16_bf16 v[34:49], v[230:233], v[170:173], v[34:49]
	ds_read_b128 v[226:229], v235 offset:4640
	v_mfma_f32_32x32x16_bf16 v[0:15], v[230:233], v[174:177], v[0:15]
	s_waitcnt lgkmcnt(1)
	v_mfma_f32_32x32x16_bf16 v[50:65], v[246:249], v[166:169], v[50:65]
	ds_read_b128 v[230:233], v235 offset:64
	v_mfma_f32_32x32x16_bf16 v[16:31], v[246:249], v[162:165], v[16:31]
	s_waitcnt lgkmcnt(1)
	v_mfma_f32_32x32x16_bf16 v[34:49], v[226:229], v[166:169], v[34:49]
	ds_read_b128 v[246:249], v235 offset:4672
	v_mfma_f32_32x32x16_bf16 v[0:15], v[226:229], v[162:165], v[0:15]
	s_waitcnt lgkmcnt(1)
	v_mfma_f32_32x32x16_bf16 v[50:65], v[230:233], v[186:189], v[50:65]
	ds_read_b128 v[226:229], v235 offset:96
	v_mfma_f32_32x32x16_bf16 v[16:31], v[230:233], v[218:221], v[16:31]
	s_waitcnt lgkmcnt(1)
	v_mfma_f32_32x32x16_bf16 v[34:49], v[246:249], v[186:189], v[34:49]
	ds_read_b128 v[230:233], v235 offset:4704
	v_mfma_f32_32x32x16_bf16 v[0:15], v[246:249], v[218:221], v[0:15]
	s_waitcnt lgkmcnt(1)
	v_mfma_f32_32x32x16_bf16 v[50:65], v[226:229], v[190:193], v[50:65]
	ds_read_b128 v[246:249], v234
	v_mfma_f32_32x32x16_bf16 v[16:31], v[226:229], v[222:225], v[16:31]
	s_waitcnt lgkmcnt(1)
	v_mfma_f32_32x32x16_bf16 v[34:49], v[230:233], v[190:193], v[34:49]
	ds_read_b128 v[226:229], v234 offset:32
	v_mfma_f32_32x32x16_bf16 v[0:15], v[230:233], v[222:225], v[0:15]
	s_waitcnt lgkmcnt(1)
	v_mfma_f32_32x32x16_bf16 v[114:129], v[246:249], v[130:133], 0
	ds_read_b128 v[230:233], v234 offset:64
	v_mfma_f32_32x32x16_bf16 v[98:113], v[246:249], v[146:149], 0
	s_waitcnt lgkmcnt(1)
	v_mfma_f32_32x32x16_bf16 v[114:129], v[226:229], v[134:137], v[114:129]
	ds_read_b128 v[246:249], v234 offset:96
	v_mfma_f32_32x32x16_bf16 v[98:113], v[226:229], v[150:153], v[98:113]
	s_waitcnt lgkmcnt(1)
	v_mfma_f32_32x32x16_bf16 v[114:129], v[230:233], v[138:141], v[114:129]
	ds_read_b128 v[226:229], v234 offset:4608
	v_mfma_f32_32x32x16_bf16 v[98:113], v[230:233], v[154:157], v[98:113]
	s_waitcnt lgkmcnt(1)
	v_mfma_f32_32x32x16_bf16 v[114:129], v[246:249], v[142:145], v[114:129]
	ds_read_b128 v[230:233], v234 offset:4640
	v_mfma_f32_32x32x16_bf16 v[98:113], v[246:249], v[158:161], v[98:113]
	s_waitcnt lgkmcnt(1)
	v_mfma_f32_32x32x16_bf16 v[82:97], v[226:229], v[130:133], 0
	ds_read_b128 v[246:249], v234 offset:4672
	v_mfma_f32_32x32x16_bf16 v[66:81], v[226:229], v[146:149], 0
	s_waitcnt lgkmcnt(1)
	v_mfma_f32_32x32x16_bf16 v[82:97], v[230:233], v[134:137], v[82:97]
	ds_read_b128 v[226:229], v234 offset:4704
	v_mfma_f32_32x32x16_bf16 v[66:81], v[230:233], v[150:153], v[66:81]
	s_waitcnt lgkmcnt(1)
	v_mfma_f32_32x32x16_bf16 v[82:97], v[246:249], v[138:141], v[82:97]
	v_mfma_f32_32x32x16_bf16 v[66:81], v[246:249], v[154:157], v[66:81]
	s_waitcnt lgkmcnt(0)
	v_mfma_f32_32x32x16_bf16 v[82:97], v[226:229], v[142:145], v[82:97]
	v_mfma_f32_32x32x16_bf16 v[66:81], v[226:229], v[158:161], v[66:81]
	s_cmp_eq_u32 s101, 1
	s_cbranch_scc0 .Lpp_nb_p1
	s_barrier
.Lpp_nb_p1:
	v_exp_f32_e32 v114, v114
	v_exp_f32_e32 v115, v115
	v_exp_f32_e32 v116, v116
	v_exp_f32_e32 v117, v117
	v_exp_f32_e32 v118, v118
	v_exp_f32_e32 v119, v119
	v_exp_f32_e32 v120, v120
	v_exp_f32_e32 v121, v121
	v_cvt_pk_bf16_f32 v170, v114, v115
	v_add_f32_e32 v114, v114, v115
	v_exp_f32_e32 v122, v122
	v_exp_f32_e32 v123, v123
	v_cvt_pk_bf16_f32 v171, v116, v117
	v_add_f32_e32 v116, v116, v117
	v_add_f32_e32 v217, v217, v114
	v_exp_f32_e32 v124, v124
	v_exp_f32_e32 v125, v125
	v_cvt_pk_bf16_f32 v172, v118, v119
	v_add_f32_e32 v118, v118, v119
	v_add_f32_e32 v217, v217, v116
	v_exp_f32_e32 v126, v126
	v_exp_f32_e32 v127, v127
	v_cvt_pk_bf16_f32 v173, v120, v121
	v_add_f32_e32 v120, v120, v121
	v_add_f32_e32 v217, v217, v118
	v_exp_f32_e32 v128, v128
	v_exp_f32_e32 v129, v129
	v_cvt_pk_bf16_f32 v166, v122, v123
	v_add_f32_e32 v122, v122, v123
	v_add_f32_e32 v217, v217, v120
	v_exp_f32_e32 v98, v98
	v_exp_f32_e32 v99, v99
	v_cvt_pk_bf16_f32 v167, v124, v125
	v_add_f32_e32 v124, v124, v125
	v_add_f32_e32 v217, v217, v122
	v_exp_f32_e32 v100, v100
	v_exp_f32_e32 v101, v101
	v_cvt_pk_bf16_f32 v168, v126, v127
	v_add_f32_e32 v126, v126, v127
	v_add_f32_e32 v217, v217, v124
	v_exp_f32_e32 v102, v102
	v_exp_f32_e32 v103, v103
	v_cvt_pk_bf16_f32 v169, v128, v129
	v_add_f32_e32 v128, v128, v129
	v_add_f32_e32 v217, v217, v126
	v_exp_f32_e32 v104, v104
	v_exp_f32_e32 v105, v105
	v_cvt_pk_bf16_f32 v174, v98, v99
	v_add_f32_e32 v98, v98, v99
	v_add_f32_e32 v217, v217, v128
	v_exp_f32_e32 v106, v106
	v_exp_f32_e32 v107, v107
	v_cvt_pk_bf16_f32 v175, v100, v101
	v_add_f32_e32 v100, v100, v101
	v_add_f32_e32 v216, v216, v98
	v_exp_f32_e32 v108, v108
	v_exp_f32_e32 v109, v109
	v_cvt_pk_bf16_f32 v176, v102, v103
	v_add_f32_e32 v102, v102, v103
	v_add_f32_e32 v216, v216, v100
	v_exp_f32_e32 v110, v110
	v_exp_f32_e32 v111, v111
	v_cvt_pk_bf16_f32 v177, v104, v105
	v_add_f32_e32 v104, v104, v105
	v_add_f32_e32 v216, v216, v102
	v_exp_f32_e32 v112, v112
	v_exp_f32_e32 v113, v113
	v_cvt_pk_bf16_f32 v162, v106, v107
	v_add_f32_e32 v106, v106, v107
	v_add_f32_e32 v216, v216, v104
	v_cvt_pk_bf16_f32 v163, v108, v109
	v_add_f32_e32 v108, v108, v109
	v_add_f32_e32 v216, v216, v106
	v_cvt_pk_bf16_f32 v164, v110, v111
	v_add_f32_e32 v110, v110, v111
	v_add_f32_e32 v216, v216, v108
	v_cvt_pk_bf16_f32 v165, v112, v113
	v_add_f32_e32 v112, v112, v113
	v_add_f32_e32 v216, v216, v110
	v_add_f32_e32 v216, v216, v112
	s_waitcnt vmcnt(0)
	s_cmp_eq_u32 s101, 0
	s_cbranch_scc0 .Lpp_nb_p2
	s_barrier
.Lpp_nb_p2:
	v_exp_f32_e32 v82, v82
	v_exp_f32_e32 v83, v83
	v_exp_f32_e32 v84, v84
	v_exp_f32_e32 v85, v85
	v_add_f32_e32 v98, 0, v82
	v_exp_f32_e32 v99, v86
	v_add_f32_e32 v98, v83, v98
	v_add_f32_e32 v98, v84, v98
	v_add_f32_e32 v98, v85, v98
	v_add_f32_e32 v86, v99, v98
	v_exp_f32_e32 v98, v87
	v_exp_f32_e32 v100, v88
	v_exp_f32_e32 v89, v89
	v_exp_f32_e32 v101, v90
	v_add_f32_e32 v86, v98, v86
	v_exp_f32_e32 v91, v91
	v_add_f32_e32 v86, v100, v86
	v_exp_f32_e32 v92, v92
	v_add_f32_e32 v86, v89, v86
	v_exp_f32_e32 v93, v93
	v_add_f32_e32 v86, v101, v86
	v_exp_f32_e32 v94, v94
	v_add_f32_e32 v86, v91, v86
	v_exp_f32_e32 v95, v95
	v_add_f32_e32 v86, v92, v86
	v_exp_f32_e32 v96, v96
	v_add_f32_e32 v86, v93, v86
	v_exp_f32_e32 v97, v97
	v_add_f32_e32 v86, v94, v86
	v_exp_f32_e32 v66, v66
	v_add_f32_e32 v86, v95, v86
	v_exp_f32_e32 v67, v67
	v_add_f32_e32 v86, v96, v86
	v_exp_f32_e32 v68, v68
	v_add_f32_e32 v86, v97, v86
	v_exp_f32_e32 v69, v69
	v_add_f32_e32 v90, v217, v86
	v_cvt_pk_bf16_f32 v86, v82, v83
	v_cvt_pk_bf16_f32 v82, v101, v91
	v_cvt_pk_bf16_f32 v83, v92, v93
	v_add_f32_e32 v91, 0, v66
	v_exp_f32_e32 v92, v70
	v_add_f32_e32 v91, v67, v91
	v_add_f32_e32 v91, v68, v91
	v_add_f32_e32 v91, v69, v91
	v_add_f32_e32 v70, v92, v91
	v_exp_f32_e32 v91, v71
	v_exp_f32_e32 v93, v72
	v_exp_f32_e32 v73, v73
	v_cvt_pk_bf16_f32 v87, v84, v85
	v_cvt_pk_bf16_f32 v84, v94, v95
	v_exp_f32_e32 v94, v74
	v_add_f32_e32 v70, v91, v70
	v_exp_f32_e32 v75, v75
	v_add_f32_e32 v70, v93, v70
	v_exp_f32_e32 v76, v76
	v_add_f32_e32 v70, v73, v70
	v_exp_f32_e32 v77, v77
	v_add_f32_e32 v70, v94, v70
	v_exp_f32_e32 v78, v78
	v_add_f32_e32 v70, v75, v70
	v_exp_f32_e32 v79, v79
	v_add_f32_e32 v70, v76, v70
	v_exp_f32_e32 v80, v80
	v_add_f32_e32 v70, v77, v70
	v_exp_f32_e32 v81, v81
	v_add_f32_e32 v70, v78, v70
	v_add_f32_e32 v70, v79, v70
	v_add_f32_e32 v70, v80, v70
	v_add_f32_e32 v70, v81, v70
	v_add_f32_e32 v74, v216, v70
	v_cvt_pk_bf16_f32 v70, v66, v67
	v_cvt_pk_bf16_f32 v71, v68, v69
	v_cvt_pk_bf16_f32 v72, v92, v91
	v_cvt_pk_bf16_f32 v73, v93, v73
	v_cvt_pk_bf16_f32 v66, v94, v75
	v_cvt_pk_bf16_f32 v67, v76, v77
	v_cvt_pk_bf16_f32 v68, v78, v79
	ds_read_b128 v[76:79], v32 offset:18432
	ds_read_b128 v[92:95], v32 offset:18464
	s_waitcnt lgkmcnt(1)
	v_mfma_f32_32x32x16_bf16 v[50:65], v[76:79], v[170:173], v[50:65]
	v_cvt_pk_bf16_f32 v88, v99, v98
	v_cvt_pk_bf16_f32 v89, v100, v89
	v_cvt_pk_bf16_f32 v85, v96, v97
	v_cvt_pk_bf16_f32 v69, v80, v81
	s_lshl_b32 s4, s39, 12
	s_add_i32 s40, s40, s4
	s_lshl_b32 s16, s1, 7
	v_mfma_f32_32x32x16_bf16 v[16:31], v[76:79], v[174:177], v[16:31]
	ds_read_b128 v[76:79], v32 offset:23040
	s_add_i32 s0, s0, s78
	s_cmpk_gt_i32 s0, 0x3ff
	s_waitcnt lgkmcnt(0)
	v_mfma_f32_32x32x16_bf16 v[34:49], v[76:79], v[170:173], v[34:49]
	v_mfma_f32_32x32x16_bf16 v[0:15], v[76:79], v[174:177], v[0:15]
	ds_read_b128 v[76:79], v32 offset:23072
	s_waitcnt lgkmcnt(0)
	v_mfma_f32_32x32x16_bf16 v[34:49], v[76:79], v[166:169], v[34:49]
	v_mfma_f32_32x32x16_bf16 v[0:15], v[76:79], v[162:165], v[0:15]
	ds_read_b128 v[76:79], v32 offset:18496
	v_mfma_f32_32x32x16_bf16 v[50:65], v[92:95], v[166:169], v[50:65]
	v_mfma_f32_32x32x16_bf16 v[16:31], v[92:95], v[162:165], v[16:31]
	s_waitcnt lgkmcnt(0)
	v_mfma_f32_32x32x16_bf16 v[50:65], v[76:79], v[86:89], v[50:65]
	v_mfma_f32_32x32x16_bf16 v[16:31], v[76:79], v[70:73], v[16:31]
	ds_read_b128 v[76:79], v32 offset:23104
	s_waitcnt lgkmcnt(0)
	v_mfma_f32_32x32x16_bf16 v[0:15], v[76:79], v[70:73], v[0:15]
	ds_read_b128 v[70:73], v32 offset:18528
	s_waitcnt lgkmcnt(0)
	v_mfma_f32_32x32x16_bf16 v[50:65], v[70:73], v[82:85], v[50:65]
	v_mfma_f32_32x32x16_bf16 v[16:31], v[70:73], v[66:69], v[16:31]
	ds_read_b128 v[70:73], v32 offset:23136
	s_waitcnt lgkmcnt(0)
	s_barrier
	v_mfma_f32_32x32x16_bf16 v[34:49], v[76:79], v[86:89], v[34:49]
	v_mfma_f32_32x32x16_bf16 v[0:15], v[70:73], v[66:69], v[0:15]
	ds_bpermute_b32 v69, v244, v90
	v_or_b32_e32 v68, s40, v202
	v_lshl_add_u64 v[66:67], v[206:207], 0, s[16:17]
	s_waitcnt lgkmcnt(0)
	v_add_f32_e32 v69, v90, v69
	v_mfma_f32_32x32x16_bf16 v[34:49], v[70:73], v[82:85], v[34:49]
	v_div_scale_f32 v70, s[4:5], v69, v69, 1.0
	v_rcp_f32_e32 v71, v70
	s_nop 0
	v_fma_f32 v72, -v70, v71, 1.0
	v_fmac_f32_e32 v71, v72, v71
	v_div_scale_f32 v72, vcc, 1.0, v69, 1.0
	v_mul_f32_e32 v73, v72, v71
	v_fma_f32 v75, -v70, v73, v72
	v_fmac_f32_e32 v73, v75, v71
	v_fma_f32 v70, -v70, v73, v72
	v_div_fmas_f32 v70, v70, v71, v73
	v_div_fixup_f32 v70, v70, v69, 1.0
	v_ashrrev_i32_e32 v69, 31, v68
	v_lshlrev_b64 v[72:73], 11, v[68:69]
	v_lshl_add_u64 v[72:73], v[66:67], 0, v[72:73]
	v_mbcnt_lo_u32_b32 v116, -1, 0
	v_mbcnt_hi_u32_b32 v116, -1, v116
	ds_bpermute_b32 v108, v244, v74
	v_and_b32_e32 v116, 32, v116
	v_lshrrev_b32_e32 v116, 2, v116
	v_mov_b32_e32 v117, 0
	v_or_b32_e32 v114, 32, v68
	v_ashrrev_i32_e32 v115, 31, v114
	v_lshlrev_b64 v[114:115], 11, v[114:115]
	v_lshl_add_u64 v[72:73], v[72:73], 0, v[116:117]
	v_lshl_add_u64 v[114:115], v[66:67], 0, v[114:115]
	v_lshl_add_u64 v[114:115], v[114:115], 0, v[116:117]
	v_pk_mul_f32 v[50:51], v[50:51], v[70:71] op_sel_hi:[1,0]
	v_pk_mul_f32 v[52:53], v[52:53], v[70:71] op_sel_hi:[1,0]
	v_pk_mul_f32 v[54:55], v[54:55], v[70:71] op_sel_hi:[1,0]
	v_pk_mul_f32 v[56:57], v[56:57], v[70:71] op_sel_hi:[1,0]
	v_cvt_pk_bf16_f32 v76, v50, v51
	v_cvt_pk_bf16_f32 v77, v52, v53
	v_cvt_pk_bf16_f32 v78, v54, v55
	v_cvt_pk_bf16_f32 v79, v56, v57
	s_nop 1
	v_permlane32_swap_b32 v76, v78
	v_permlane32_swap_b32 v77, v79
	global_store_dwordx4 v[72:73], v[76:79], off
	v_pk_mul_f32 v[58:59], v[58:59], v[70:71] op_sel_hi:[1,0]
	v_pk_mul_f32 v[60:61], v[60:61], v[70:71] op_sel_hi:[1,0]
	v_pk_mul_f32 v[62:63], v[62:63], v[70:71] op_sel_hi:[1,0]
	v_pk_mul_f32 v[64:65], v[64:65], v[70:71] op_sel_hi:[1,0]
	v_cvt_pk_bf16_f32 v80, v58, v59
	v_cvt_pk_bf16_f32 v81, v60, v61
	v_cvt_pk_bf16_f32 v82, v62, v63
	v_cvt_pk_bf16_f32 v83, v64, v65
	s_nop 1
	v_permlane32_swap_b32 v80, v82
	v_permlane32_swap_b32 v81, v83
	global_store_dwordx4 v[72:73], v[80:83], off offset:32
	s_waitcnt lgkmcnt(0)
	v_add_f32_e32 v108, v74, v108
	v_div_scale_f32 v109, s[4:5], v108, v108, 1.0
	v_rcp_f32_e32 v110, v109
	s_nop 0
	v_fma_f32 v111, -v109, v110, 1.0
	v_fmac_f32_e32 v110, v111, v110
	v_div_scale_f32 v111, vcc, 1.0, v108, 1.0
	v_mul_f32_e32 v112, v111, v110
	v_fma_f32 v113, -v109, v112, v111
	v_fmac_f32_e32 v112, v113, v110
	v_fma_f32 v109, -v109, v112, v111
	v_div_fmas_f32 v109, v109, v110, v112
	v_div_fixup_f32 v108, v109, v108, 1.0
	v_pk_mul_f32 v[34:35], v[34:35], v[70:71] op_sel_hi:[1,0]
	v_pk_mul_f32 v[36:37], v[36:37], v[70:71] op_sel_hi:[1,0]
	v_pk_mul_f32 v[38:39], v[38:39], v[70:71] op_sel_hi:[1,0]
	v_pk_mul_f32 v[40:41], v[40:41], v[70:71] op_sel_hi:[1,0]
	v_cvt_pk_bf16_f32 v84, v34, v35
	v_cvt_pk_bf16_f32 v85, v36, v37
	v_cvt_pk_bf16_f32 v86, v38, v39
	v_cvt_pk_bf16_f32 v87, v40, v41
	s_nop 1
	v_permlane32_swap_b32 v84, v86
	v_permlane32_swap_b32 v85, v87
	global_store_dwordx4 v[72:73], v[84:87], off offset:64
	v_pk_mul_f32 v[42:43], v[42:43], v[70:71] op_sel_hi:[1,0]
	v_pk_mul_f32 v[44:45], v[44:45], v[70:71] op_sel_hi:[1,0]
	v_pk_mul_f32 v[46:47], v[46:47], v[70:71] op_sel_hi:[1,0]
	v_pk_mul_f32 v[48:49], v[48:49], v[70:71] op_sel_hi:[1,0]
	v_cvt_pk_bf16_f32 v88, v42, v43
	v_cvt_pk_bf16_f32 v89, v44, v45
	v_cvt_pk_bf16_f32 v90, v46, v47
	v_cvt_pk_bf16_f32 v91, v48, v49
	s_nop 1
	v_permlane32_swap_b32 v88, v90
	v_permlane32_swap_b32 v89, v91
	global_store_dwordx4 v[72:73], v[88:91], off offset:96
	v_pk_mul_f32 v[16:17], v[16:17], v[108:109] op_sel_hi:[1,0]
	v_pk_mul_f32 v[18:19], v[18:19], v[108:109] op_sel_hi:[1,0]
	v_pk_mul_f32 v[20:21], v[20:21], v[108:109] op_sel_hi:[1,0]
	v_pk_mul_f32 v[22:23], v[22:23], v[108:109] op_sel_hi:[1,0]
	v_cvt_pk_bf16_f32 v92, v16, v17
	v_cvt_pk_bf16_f32 v93, v18, v19
	v_cvt_pk_bf16_f32 v94, v20, v21
	v_cvt_pk_bf16_f32 v95, v22, v23
	s_nop 1
	v_permlane32_swap_b32 v92, v94
	v_permlane32_swap_b32 v93, v95
	global_store_dwordx4 v[114:115], v[92:95], off
	v_pk_mul_f32 v[24:25], v[24:25], v[108:109] op_sel_hi:[1,0]
	v_pk_mul_f32 v[26:27], v[26:27], v[108:109] op_sel_hi:[1,0]
	v_pk_mul_f32 v[28:29], v[28:29], v[108:109] op_sel_hi:[1,0]
	v_pk_mul_f32 v[30:31], v[30:31], v[108:109] op_sel_hi:[1,0]
	v_cvt_pk_bf16_f32 v96, v24, v25
	v_cvt_pk_bf16_f32 v97, v26, v27
	v_cvt_pk_bf16_f32 v98, v28, v29
	v_cvt_pk_bf16_f32 v99, v30, v31
	s_nop 1
	v_permlane32_swap_b32 v96, v98
	v_permlane32_swap_b32 v97, v99
	global_store_dwordx4 v[114:115], v[96:99], off offset:32
	v_pk_mul_f32 v[0:1], v[0:1], v[108:109] op_sel_hi:[1,0]
	v_pk_mul_f32 v[2:3], v[2:3], v[108:109] op_sel_hi:[1,0]
	v_pk_mul_f32 v[4:5], v[4:5], v[108:109] op_sel_hi:[1,0]
	v_pk_mul_f32 v[6:7], v[6:7], v[108:109] op_sel_hi:[1,0]
	v_cvt_pk_bf16_f32 v100, v0, v1
	v_cvt_pk_bf16_f32 v101, v2, v3
	v_cvt_pk_bf16_f32 v102, v4, v5
	v_cvt_pk_bf16_f32 v103, v6, v7
	s_nop 1
	v_permlane32_swap_b32 v100, v102
	v_permlane32_swap_b32 v101, v103
	global_store_dwordx4 v[114:115], v[100:103], off offset:64
	v_pk_mul_f32 v[8:9], v[8:9], v[108:109] op_sel_hi:[1,0]
	v_pk_mul_f32 v[10:11], v[10:11], v[108:109] op_sel_hi:[1,0]
	v_pk_mul_f32 v[12:13], v[12:13], v[108:109] op_sel_hi:[1,0]
	v_pk_mul_f32 v[14:15], v[14:15], v[108:109] op_sel_hi:[1,0]
	v_cvt_pk_bf16_f32 v104, v8, v9
	v_cvt_pk_bf16_f32 v105, v10, v11
	v_cvt_pk_bf16_f32 v106, v12, v13
	v_cvt_pk_bf16_f32 v107, v14, v15
	s_nop 1
	v_permlane32_swap_b32 v104, v106
	v_permlane32_swap_b32 v105, v107
	global_store_dwordx4 v[114:115], v[104:107], off offset:96
	s_cbranch_scc0 .LBB0_1012
	v_mov_b32_e32 v246, 0x60
	v_mov_b64_e32 v[248:249], 0x300
	v_mov_b64_e32 v[250:251], 0x2ff
